# attention tile loop: one static s_setprio 1 for waves 4-7 (younger half), reset at loop exit
# baseline (speedup 1.0000x reference)
; #define LAS __attribute__((address_space(3)))
; __device__ __forceinline__ void attn_unit(const bf16_t* Q, const bf16_t* K, const bf16_t* Vt, int ntiles, int nrows, bf16_t* O, float negM, LAS unsigned char* lds, int tid) {
;     const int lane = tid & 63, w = tid >> 6, r32 = lane & 31, hi = lane >> 5;
;     const int row0 = w * 64 + r32, row1 = row0 + 32;
;     bf16x8 qa[4], qb[4];
;     {
;         const bf16_t* qp0 = Q + (size_t)min(row0, nrows - 1) * 64 + hi * 8;
;         const bf16_t* qp1 = Q + (size_t)min(row1, nrows - 1) * 64 + hi * 8;
; #pragma unroll
;         for (int s = 0; s < 4; ++s) { qa[s] = *(const bf16x8*)(qp0 + 16 * s); qb[s] = *(const bf16x8*)(qp1 + 16 * s); }
;     }
;     LAS unsigned char* qlds = lds + 40960 + w * 4096 + lane * 16;
; #pragma unroll
;     for (int s = 0; s < 4; ++s) *(LAS bf16x8*)(qlds + s * 1024) = qb[s];
;     f32x16 oa0, oa1, ob0, ob1;
; #pragma unroll
;     for (int e = 0; e < 16; ++e) { oa0[e] = 0.f; oa1[e] = 0.f; ob0[e] = 0.f; ob1[e] = 0.f; }
;     float lsa = 0.f, lsb = 0.f;
;     const int srow = tid >> 3, sch = tid & 7;
;     const bf16_t* kg = K + srow * 64 + sch * 8;
;     const bf16_t* vg = Vt + (size_t)srow * TKV + sch * 8;
;     const int soff = srow * 144 + sch * 16;
;     u32x4 kr = *(const u32x4*)kg, vr = *(const u32x4*)vg;
;     *(LAS u32x4*)(lds + soff) = kr; *(LAS u32x4*)(lds + 9216 + soff) = vr;
;     __syncthreads();
;     const int foff = r32 * 144 + hi * 16;
;     ...
;     asm volatile("" : "+s"(ntiles));
.Lattn_noremap:
	s_add_i32 s4, s7, 0xfffffe00
	s_cmpk_lt_i32 s7, 0x200
	s_cselect_b64 s[0:1], -1, 0
	s_and_b64 s[0:1], s[0:1], exec
	s_cselect_b32 s4, s7, s4
	s_cselect_b32 s8, s14, 0x100
	s_cselect_b32 s13, 0x44, 4
	s_lshl_b32 s0, s4, 9
	s_and_b32 s9, s0, 0xe00
	s_or_b32 s5, s9, 0x100
	s_cmpk_lt_i32 s7, 0x200
	s_cselect_b64 s[0:1], -1, 0
	s_and_b64 s[0:1], s[0:1], exec
	s_cselect_b32 s28, s5, 0
	s_ashr_i32 s10, s4, 3
	s_cmpk_lt_i32 s7, 0x200
	s_cselect_b64 s[0:1], -1, 0
	s_and_b64 s[0:1], s[0:1], exec
	s_cselect_b32 s29, s10, s7
	s_ashr_i32 s12, s7, 6
	s_cmpk_lt_i32 s7, 0x200
	s_cselect_b64 s[0:1], -1, 0
	s_and_b64 s[4:5], s[0:1], exec
	s_cselect_b32 s5, s12, s10
	s_and_b32 s11, s29, 7
	s_bfe_u32 s4, s29, 0x10002
	s_lshl_b32 s29, s5, 3
	s_or_b32 s29, s29, s11
	s_mul_hi_i32 s30, s29, 0x1100
	s_mulk_i32 s29, 0x1100
	s_add_u32 s28, s29, s28
	s_addc_u32 s29, s30, 0
	s_lshl_b64 s[28:29], s[28:29], 7
	s_add_u32 s28, s34, s28
	s_addc_u32 s29, s35, s29
	s_add_i32 s31, s8, -1
	v_min_i32_e32 v16, s31, v170
	v_ashrrev_i32_e32 v17, 31, v16
	v_lshlrev_b64 v[16:17], 7, v[16:17]
	v_lshl_add_u64 v[16:17], s[28:29], 0, v[16:17]
	v_lshl_add_u64 v[28:29], v[16:17], 0, v[186:187]
	v_min_i32_e32 v16, s31, v172
	v_ashrrev_i32_e32 v17, 31, v16
	v_lshlrev_b64 v[16:17], 7, v[16:17]
	v_lshl_add_u64 v[16:17], s[28:29], 0, v[16:17]
	v_lshl_add_u64 v[30:31], v[16:17], 0, v[186:187]
	global_load_dwordx4 v[146:149], v[28:29], off
	global_load_dwordx4 v[150:153], v[28:29], off offset:32
	global_load_dwordx4 v[154:157], v[28:29], off offset:64
	global_load_dwordx4 v[158:161], v[28:29], off offset:96
	global_load_dwordx4 v[96:99], v[30:31], off
	global_load_dwordx4 v[100:103], v[30:31], off offset:32
	global_load_dwordx4 v[104:107], v[30:31], off offset:64
	global_load_dwordx4 v[108:111], v[30:31], off offset:96
	s_lshl_b32 s5, s5, 1
	s_or_b32 s30, s4, s5
	v_mad_i64_i32 v[112:113], s[28:29], s30, v233, v[174:175]
	v_mad_i64_i32 v[114:115], s[28:29], s30, v233, v[176:177]
	global_load_dwordx4 v[162:165], v[112:113], off
	global_load_dwordx4 v[166:169], v[114:115], off
	v_mad_i64_i32 v[196:197], s[4:5], s30, v233, v[184:185]
	v_mad_i64_i32 v[198:199], s[4:5], s30, v233, v[192:193]
	v_mov_b32_e32 v173, v181
	s_movk_i32 s28, 0x4800
	v_add_u32_e32 v188, s28, v181
	s_mov_b32 s29, 0
	v_mov_b32_e32 v194, 0
	v_mov_b32_e32 v195, 0
	v_mov_b32_e32 v226, 0
	v_mov_b32_e32 v227, 0
	v_mov_b32_e32 v246, 0
	v_mov_b32_e32 v247, 0
	v_mov_b32_e32 v16, 0
	v_mov_b32_e32 v17, 0
	v_mov_b32_e32 v18, 0
	v_mov_b32_e32 v19, 0
	v_mov_b32_e32 v20, 0
	v_mov_b32_e32 v21, 0
	v_mov_b32_e32 v22, 0
	v_mov_b32_e32 v23, 0
	v_mov_b32_e32 v24, 0
	v_mov_b32_e32 v25, 0
	v_mov_b32_e32 v26, 0
	v_mov_b32_e32 v27, 0
	v_mov_b32_e32 v28, 0
	v_mov_b32_e32 v29, 0
	v_mov_b32_e32 v30, 0
	v_mov_b32_e32 v31, 0
	v_mov_b32_e32 v32, 0
	v_mov_b32_e32 v33, 0
	v_mov_b32_e32 v34, 0
	v_mov_b32_e32 v35, 0
	v_mov_b32_e32 v36, 0
	v_mov_b32_e32 v37, 0
	v_mov_b32_e32 v38, 0
	v_mov_b32_e32 v39, 0
	v_mov_b32_e32 v40, 0
	v_mov_b32_e32 v41, 0
	v_mov_b32_e32 v42, 0
	v_mov_b32_e32 v43, 0
	v_mov_b32_e32 v44, 0
	v_mov_b32_e32 v45, 0
	v_mov_b32_e32 v46, 0
	v_mov_b32_e32 v47, 0
	v_mov_b32_e32 v48, 0
	v_mov_b32_e32 v49, 0
	v_mov_b32_e32 v50, 0
	v_mov_b32_e32 v51, 0
	v_mov_b32_e32 v52, 0
	v_mov_b32_e32 v53, 0
	v_mov_b32_e32 v54, 0
	v_mov_b32_e32 v55, 0
	v_mov_b32_e32 v56, 0
	v_mov_b32_e32 v57, 0
	v_mov_b32_e32 v58, 0
	v_mov_b32_e32 v59, 0
	v_mov_b32_e32 v60, 0
	v_mov_b32_e32 v61, 0
	v_mov_b32_e32 v62, 0
	v_mov_b32_e32 v63, 0
	v_mov_b32_e32 v64, 0
	v_mov_b32_e32 v65, 0
	v_mov_b32_e32 v66, 0
	v_mov_b32_e32 v67, 0
	v_mov_b32_e32 v68, 0
	v_mov_b32_e32 v69, 0
	v_mov_b32_e32 v70, 0
	v_mov_b32_e32 v71, 0
	v_mov_b32_e32 v72, 0
	v_mov_b32_e32 v73, 0
	v_mov_b32_e32 v74, 0
	v_mov_b32_e32 v75, 0
	v_mov_b32_e32 v76, 0
	v_mov_b32_e32 v77, 0
	v_mov_b32_e32 v78, 0
	v_mov_b32_e32 v79, 0
	v_mov_b32_e32 v238, 0
	v_mov_b32_e32 v239, 0
	v_mov_b32_e32 v240, 0
	v_mov_b32_e32 v241, 0
	v_mov_b32_e32 v242, 0
	v_mov_b32_e32 v243, 0
	v_mov_b32_e32 v244, 0
	v_mov_b32_e32 v245, 0
	s_waitcnt vmcnt(0)
	ds_write_b128 v145, v[162:165]
	ds_write_b128 v145, v[166:169] offset:9216
	global_load_dwordx4 v[162:165], v[198:199], off
	global_load_dwordx4 v[166:169], v[196:197], off
	v_lshl_add_u64 v[198:199], v[198:199], 0, s[80:81]
	v_lshl_add_u64 v[196:197], v[196:197], 0, s[44:45]
	s_waitcnt lgkmcnt(0)
	s_barrier
	ds_read_b128 v[80:83], v173
	ds_read_b128 v[84:87], v173 offset:32
	ds_read_b128 v[88:91], v173 offset:64
	ds_read_b128 v[92:95], v173 offset:96
	ds_read_b128 v[200:203], v173 offset:9280
	ds_read_b128 v[204:207], v173 offset:13888
	ds_read_b128 v[208:211], v173 offset:9312
	ds_read_b128 v[212:215], v173 offset:13920
	s_waitcnt lgkmcnt(7)
	v_mfma_f32_32x32x16_bf16 v[112:127], v[80:83], v[146:149], v[0:15]
	s_waitcnt lgkmcnt(6)
	v_mfma_f32_32x32x16_bf16 v[112:127], v[84:87], v[150:153], v[112:127]
	s_waitcnt lgkmcnt(5)
	v_mfma_f32_32x32x16_bf16 v[112:127], v[88:91], v[154:157], v[112:127]
	s_waitcnt lgkmcnt(4)
	v_mfma_f32_32x32x16_bf16 v[112:127], v[92:95], v[158:161], v[112:127]
	s_waitcnt lgkmcnt(0)
	s_nop 7
	s_nop 3
	v_cmp_lt_u32_e32 vcc, 0xff, v144
	s_cbranch_vccz .Lattn_noprio
	s_setprio 1
; #define LAS __attribute__((address_space(3)))
; __device__ __forceinline__ void attn_unit(const bf16_t* Q, const bf16_t* K, const bf16_t* Vt, int ntiles, int nrows, bf16_t* O, float negM, LAS unsigned char* lds, int tid) {
;     ...
;     for (int t = 0; t < ntiles; ++t) {
;         const int cur = t & 1;
;         const bool more = (t + 1 < ntiles);
;         if (more) { kr = *(const u32x4*)(kg + (size_t)(t + 1) * 4096); vr = *(const u32x4*)(vg + (size_t)(t + 1) * 64); }
;         const LAS unsigned char* kb = lds + cur * 18432 + foff;
;         const LAS unsigned char* vb = kb + 9216;
;         bf16x8 kf0[4], kf1[4];
; #pragma unroll
;         for (int s = 0; s < 4; ++s) { kf0[s] = *(const LAS bf16x8*)(kb + s * 32); kf1[s] = *(const LAS bf16x8*)(kb + 32 * 144 + s * 32); }
;         bf16x8 pa[4], pb[4];
;         ATT_SCORES(qa, pa, lsa);
;         bf16x8 qc[4];
; #pragma unroll
;         for (int s = 0; s < 4; ++s) qc[s] = *(const LAS bf16x8*)(qlds + s * 1024);
;         ATT_SCORES(qc, pb, lsb);
; #pragma unroll
;         for (int s = 0; s < 4; ++s) {
;             const bf16x8 v0 = *(const LAS bf16x8*)(vb + s * 32), v1 = *(const LAS bf16x8*)(vb + 32 * 144 + s * 32);
;             oa0 = __builtin_amdgcn_mfma_f32_32x32x16_bf16(v0, pa[s], oa0, 0, 0, 0);
;             oa1 = __builtin_amdgcn_mfma_f32_32x32x16_bf16(v1, pa[s], oa1, 0, 0, 0);
;             ob0 = __builtin_amdgcn_mfma_f32_32x32x16_bf16(v0, pb[s], ob0, 0, 0, 0);
;             ob1 = __builtin_amdgcn_mfma_f32_32x32x16_bf16(v1, pb[s], ob1, 0, 0, 0);
;         }
;         if (more) { *(LAS u32x4*)(lds + (cur ^ 1) * 18432 + soff) = kr; *(LAS u32x4*)(lds + (cur ^ 1) * 18432 + 9216 + soff) = vr; }
;         __syncthreads();
;     }
.Lattn_noprio:
.Lattn_tile:
	v_mfma_f32_32x32x16_bf16 v[128:143], v[80:83], v[96:99], v[0:15]
	ds_read_b128 v[80:83], v173 offset:4608
	v_exp_f32_e32 v112, v112
	v_exp_f32_e32 v113, v113
	v_mfma_f32_32x32x16_bf16 v[16:31], v[200:203], v[238:241], v[16:31]
	ds_read_b128 v[200:203], v173 offset:9216
	v_exp_f32_e32 v114, v114
	v_exp_f32_e32 v115, v115
	v_cvt_pk_bf16_f32 v216, v112, v113
	v_add_f32_e32 v194, v194, v112
	v_add_f32_e32 v226, v226, v113
	v_mfma_f32_32x32x16_bf16 v[128:143], v[84:87], v[100:103], v[128:143]
	ds_read_b128 v[84:87], v173 offset:4640
	v_exp_f32_e32 v116, v116
	v_exp_f32_e32 v117, v117
	v_cvt_pk_bf16_f32 v217, v114, v115
	v_add_f32_e32 v194, v194, v114
	v_add_f32_e32 v226, v226, v115
	v_mfma_f32_32x32x16_bf16 v[32:47], v[204:207], v[238:241], v[32:47]
	ds_read_b128 v[204:207], v173 offset:13824
	v_exp_f32_e32 v118, v118
	v_exp_f32_e32 v119, v119
	v_cvt_pk_bf16_f32 v218, v116, v117
	v_add_f32_e32 v194, v194, v116
	v_add_f32_e32 v226, v226, v117
	v_mfma_f32_32x32x16_bf16 v[128:143], v[88:91], v[104:107], v[128:143]
	ds_read_b128 v[88:91], v173 offset:4672
	v_exp_f32_e32 v120, v120
	v_exp_f32_e32 v121, v121
	v_cvt_pk_bf16_f32 v219, v118, v119
	v_add_f32_e32 v194, v194, v118
	v_add_f32_e32 v226, v226, v119
	v_mfma_f32_32x32x16_bf16 v[16:31], v[208:211], v[242:245], v[16:31]
	ds_read_b128 v[208:211], v173 offset:9248
	v_exp_f32_e32 v122, v122
	v_exp_f32_e32 v123, v123
	v_cvt_pk_bf16_f32 v234, v120, v121
	v_add_f32_e32 v194, v194, v120
	v_add_f32_e32 v226, v226, v121
	v_mfma_f32_32x32x16_bf16 v[128:143], v[92:95], v[108:111], v[128:143]
	ds_read_b128 v[92:95], v173 offset:4704
	v_exp_f32_e32 v124, v124
	v_exp_f32_e32 v125, v125
	v_cvt_pk_bf16_f32 v235, v122, v123
	v_add_f32_e32 v194, v194, v122
	v_add_f32_e32 v226, v226, v123
	v_mfma_f32_32x32x16_bf16 v[32:47], v[212:215], v[242:245], v[32:47]
	ds_read_b128 v[212:215], v173 offset:13856
	v_exp_f32_e32 v126, v126
	v_exp_f32_e32 v127, v127
	v_cvt_pk_bf16_f32 v236, v124, v125
	v_add_f32_e32 v194, v194, v124
	v_add_f32_e32 v226, v226, v125
	v_cvt_pk_bf16_f32 v237, v126, v127
	v_add_f32_e32 v194, v194, v126
	v_add_f32_e32 v226, v226, v127
	s_waitcnt vmcnt(0)
	v_add_u32_e32 v189, s28, v145
	ds_write_b128 v189, v[162:165]
	ds_write_b128 v189, v[166:169] offset:9216
	global_load_dwordx4 v[162:165], v[198:199], off
	global_load_dwordx4 v[166:169], v[196:197], off
	v_lshl_add_u64 v[198:199], v[198:199], 0, s[80:81]
	v_lshl_add_u64 v[196:197], v[196:197], 0, s[44:45]
	s_waitcnt lgkmcnt(8)
	v_mfma_f32_32x32x16_bf16 v[112:127], v[80:83], v[146:149], v[0:15]
	v_exp_f32_e32 v128, v128
	v_exp_f32_e32 v129, v129
	v_mfma_f32_32x32x16_bf16 v[48:63], v[200:203], v[216:219], v[48:63]
	v_exp_f32_e32 v130, v130
	v_exp_f32_e32 v131, v131
	v_cvt_pk_bf16_f32 v238, v128, v129
	v_add_f32_e32 v195, v195, v128
	v_add_f32_e32 v227, v227, v129
	s_waitcnt lgkmcnt(6)
	v_mfma_f32_32x32x16_bf16 v[112:127], v[84:87], v[150:153], v[112:127]
	v_exp_f32_e32 v132, v132
	v_exp_f32_e32 v133, v133
	v_cvt_pk_bf16_f32 v239, v130, v131
	v_add_f32_e32 v195, v195, v130
	v_add_f32_e32 v227, v227, v131
	v_mfma_f32_32x32x16_bf16 v[64:79], v[204:207], v[216:219], v[64:79]
	v_exp_f32_e32 v134, v134
	v_exp_f32_e32 v135, v135
	v_cvt_pk_bf16_f32 v240, v132, v133
	v_add_f32_e32 v195, v195, v132
	v_add_f32_e32 v227, v227, v133
	s_waitcnt lgkmcnt(4)
	v_mfma_f32_32x32x16_bf16 v[112:127], v[88:91], v[154:157], v[112:127]
	v_exp_f32_e32 v136, v136
	v_exp_f32_e32 v137, v137
	v_cvt_pk_bf16_f32 v241, v134, v135
	v_add_f32_e32 v195, v195, v134
	v_add_f32_e32 v227, v227, v135
	v_mfma_f32_32x32x16_bf16 v[48:63], v[208:211], v[234:237], v[48:63]
	v_exp_f32_e32 v138, v138
	v_exp_f32_e32 v139, v139
	v_cvt_pk_bf16_f32 v242, v136, v137
	v_add_f32_e32 v195, v195, v136
	v_add_f32_e32 v227, v227, v137
	s_waitcnt lgkmcnt(2)
	v_mfma_f32_32x32x16_bf16 v[112:127], v[92:95], v[158:161], v[112:127]
	v_exp_f32_e32 v140, v140
	v_exp_f32_e32 v141, v141
	v_cvt_pk_bf16_f32 v243, v138, v139
	v_add_f32_e32 v195, v195, v138
	v_add_f32_e32 v227, v227, v139
	v_mfma_f32_32x32x16_bf16 v[64:79], v[212:215], v[234:237], v[64:79]
	v_exp_f32_e32 v142, v142
	v_exp_f32_e32 v143, v143
	v_cvt_pk_bf16_f32 v244, v140, v141
	v_add_f32_e32 v195, v195, v140
	v_add_f32_e32 v227, v227, v141
	v_cvt_pk_bf16_f32 v245, v142, v143
	v_add_f32_e32 v195, v195, v142
	v_add_f32_e32 v227, v227, v143
	s_waitcnt lgkmcnt(0)
	s_barrier
; #define LAS __attribute__((address_space(3)))
; __device__ __forceinline__ void attn_unit(const bf16_t* Q, const bf16_t* K, const bf16_t* Vt, int ntiles, int nrows, bf16_t* O, float negM, LAS unsigned char* lds, int tid) {
;     ...
;     for (int t = 0; t < ntiles; ++t) {
;         const int cur = t & 1;
;         const bool more = (t + 1 < ntiles);
;         if (more) { kr = *(const u32x4*)(kg + (size_t)(t + 1) * 4096); vr = *(const u32x4*)(vg + (size_t)(t + 1) * 64); }
;         const LAS unsigned char* kb = lds + cur * 18432 + foff;
;         const LAS unsigned char* vb = kb + 9216;
;         bf16x8 kf0[4], kf1[4];
; #pragma unroll
;         for (int s = 0; s < 4; ++s) { kf0[s] = *(const LAS bf16x8*)(kb + s * 32); kf1[s] = *(const LAS bf16x8*)(kb + 32 * 144 + s * 32); }
;         bf16x8 pa[4], pb[4];
;         ATT_SCORES(qa, pa, lsa);
;         bf16x8 qc[4];
; #pragma unroll
;         for (int s = 0; s < 4; ++s) qc[s] = *(const LAS bf16x8*)(qlds + s * 1024);
;         ATT_SCORES(qc, pb, lsb);
; #pragma unroll
;         for (int s = 0; s < 4; ++s) {
;             const bf16x8 v0 = *(const LAS bf16x8*)(vb + s * 32), v1 = *(const LAS bf16x8*)(vb + 32 * 144 + s * 32);
;             oa0 = __builtin_amdgcn_mfma_f32_32x32x16_bf16(v0, pa[s], oa0, 0, 0, 0);
;             oa1 = __builtin_amdgcn_mfma_f32_32x32x16_bf16(v1, pa[s], oa1, 0, 0, 0);
;             ob0 = __builtin_amdgcn_mfma_f32_32x32x16_bf16(v0, pb[s], ob0, 0, 0, 0);
;             ob1 = __builtin_amdgcn_mfma_f32_32x32x16_bf16(v1, pb[s], ob1, 0, 0, 0);
;         }
;         if (more) { *(LAS u32x4*)(lds + (cur ^ 1) * 18432 + soff) = kr; *(LAS u32x4*)(lds + (cur ^ 1) * 18432 + 9216 + soff) = vr; }
;         __syncthreads();
;     }
	v_mfma_f32_32x32x16_bf16 v[128:143], v[80:83], v[96:99], v[0:15]
	ds_read_b128 v[80:83], v188
	v_exp_f32_e32 v112, v112
	v_exp_f32_e32 v113, v113
	v_mfma_f32_32x32x16_bf16 v[16:31], v[200:203], v[238:241], v[16:31]
	ds_read_b128 v[200:203], v173 offset:9280
	v_exp_f32_e32 v114, v114
	v_exp_f32_e32 v115, v115
	v_cvt_pk_bf16_f32 v216, v112, v113
	v_add_f32_e32 v194, v194, v112
	v_add_f32_e32 v226, v226, v113
	v_mfma_f32_32x32x16_bf16 v[128:143], v[84:87], v[100:103], v[128:143]
	ds_read_b128 v[84:87], v188 offset:32
	v_exp_f32_e32 v116, v116
	v_exp_f32_e32 v117, v117
	v_cvt_pk_bf16_f32 v217, v114, v115
	v_add_f32_e32 v194, v194, v114
	v_add_f32_e32 v226, v226, v115
	v_mfma_f32_32x32x16_bf16 v[32:47], v[204:207], v[238:241], v[32:47]
	ds_read_b128 v[204:207], v173 offset:13888
	v_exp_f32_e32 v118, v118
	v_exp_f32_e32 v119, v119
	v_cvt_pk_bf16_f32 v218, v116, v117
	v_add_f32_e32 v194, v194, v116
	v_add_f32_e32 v226, v226, v117
	v_mfma_f32_32x32x16_bf16 v[128:143], v[88:91], v[104:107], v[128:143]
	ds_read_b128 v[88:91], v188 offset:64
	v_exp_f32_e32 v120, v120
	v_exp_f32_e32 v121, v121
	v_cvt_pk_bf16_f32 v219, v118, v119
	v_add_f32_e32 v194, v194, v118
	v_add_f32_e32 v226, v226, v119
	v_mfma_f32_32x32x16_bf16 v[16:31], v[208:211], v[242:245], v[16:31]
	ds_read_b128 v[208:211], v173 offset:9312
	v_exp_f32_e32 v122, v122
	v_exp_f32_e32 v123, v123
	v_cvt_pk_bf16_f32 v234, v120, v121
	v_add_f32_e32 v194, v194, v120
	v_add_f32_e32 v226, v226, v121
	v_mfma_f32_32x32x16_bf16 v[128:143], v[92:95], v[108:111], v[128:143]
	ds_read_b128 v[92:95], v188 offset:96
	v_exp_f32_e32 v124, v124
	v_exp_f32_e32 v125, v125
	v_cvt_pk_bf16_f32 v235, v122, v123
	v_add_f32_e32 v194, v194, v122
	v_add_f32_e32 v226, v226, v123
	v_mfma_f32_32x32x16_bf16 v[32:47], v[212:215], v[242:245], v[32:47]
	ds_read_b128 v[212:215], v173 offset:13920
	v_exp_f32_e32 v126, v126
	v_exp_f32_e32 v127, v127
	v_cvt_pk_bf16_f32 v236, v124, v125
	v_add_f32_e32 v194, v194, v124
	v_add_f32_e32 v226, v226, v125
	v_cvt_pk_bf16_f32 v237, v126, v127
	v_add_f32_e32 v194, v194, v126
	v_add_f32_e32 v226, v226, v127
	s_waitcnt lgkmcnt(6)
	v_mfma_f32_32x32x16_bf16 v[112:127], v[80:83], v[146:149], v[0:15]
	v_exp_f32_e32 v128, v128
	v_exp_f32_e32 v129, v129
	v_mfma_f32_32x32x16_bf16 v[48:63], v[200:203], v[216:219], v[48:63]
	v_exp_f32_e32 v130, v130
	v_exp_f32_e32 v131, v131
	v_cvt_pk_bf16_f32 v238, v128, v129
	v_add_f32_e32 v195, v195, v128
	v_add_f32_e32 v227, v227, v129
	s_waitcnt lgkmcnt(4)
	v_mfma_f32_32x32x16_bf16 v[112:127], v[84:87], v[150:153], v[112:127]
	v_exp_f32_e32 v132, v132
	v_exp_f32_e32 v133, v133
	v_cvt_pk_bf16_f32 v239, v130, v131
	v_add_f32_e32 v195, v195, v130
	v_add_f32_e32 v227, v227, v131
	v_mfma_f32_32x32x16_bf16 v[64:79], v[204:207], v[216:219], v[64:79]
	v_exp_f32_e32 v134, v134
	v_exp_f32_e32 v135, v135
	v_cvt_pk_bf16_f32 v240, v132, v133
	v_add_f32_e32 v195, v195, v132
	v_add_f32_e32 v227, v227, v133
	s_waitcnt lgkmcnt(2)
	v_mfma_f32_32x32x16_bf16 v[112:127], v[88:91], v[154:157], v[112:127]
	v_exp_f32_e32 v136, v136
	v_exp_f32_e32 v137, v137
	v_cvt_pk_bf16_f32 v241, v134, v135
	v_add_f32_e32 v195, v195, v134
	v_add_f32_e32 v227, v227, v135
	v_mfma_f32_32x32x16_bf16 v[48:63], v[208:211], v[234:237], v[48:63]
	v_exp_f32_e32 v138, v138
	v_exp_f32_e32 v139, v139
	v_cvt_pk_bf16_f32 v242, v136, v137
	v_add_f32_e32 v195, v195, v136
	v_add_f32_e32 v227, v227, v137
	s_waitcnt lgkmcnt(0)
	v_mfma_f32_32x32x16_bf16 v[112:127], v[92:95], v[158:161], v[112:127]
	v_exp_f32_e32 v140, v140
	v_exp_f32_e32 v141, v141
	v_cvt_pk_bf16_f32 v243, v138, v139
	v_add_f32_e32 v195, v195, v138
	v_add_f32_e32 v227, v227, v139
	v_mfma_f32_32x32x16_bf16 v[64:79], v[212:215], v[234:237], v[64:79]
	v_exp_f32_e32 v142, v142
	v_exp_f32_e32 v143, v143
	v_cvt_pk_bf16_f32 v244, v140, v141
	v_add_f32_e32 v195, v195, v140
	v_add_f32_e32 v227, v227, v141
	v_cvt_pk_bf16_f32 v245, v142, v143
	v_add_f32_e32 v195, v195, v142
	v_add_f32_e32 v227, v227, v143
	v_mov_b32_e32 v173, v188
	s_add_i32 s28, s28, 0x4800
	s_cmp_eq_u32 s28, 0xd800
	s_cselect_b32 s28, 0, s28
	v_add_u32_e32 v188, s28, v181
	s_add_i32 s29, s29, 1
	s_cmp_lt_i32 s29, s13
	s_cbranch_scc1 .Lattn_tile
	s_setprio 0
	s_waitcnt lgkmcnt(0)
	s_barrier
	v_mfma_f32_32x32x16_bf16 v[16:31], v[200:203], v[238:241], v[16:31]
	v_mfma_f32_32x32x16_bf16 v[32:47], v[204:207], v[238:241], v[32:47]
	v_mfma_f32_32x32x16_bf16 v[16:31], v[208:211], v[242:245], v[16:31]
	v_mfma_f32_32x32x16_bf16 v[32:47], v[212:215], v[242:245], v[32:47]
	v_add_f32_e32 v194, v194, v226
	v_add_f32_e32 v195, v195, v227
	s_nop 7
	s_nop 3
